# speedup vs baseline: 1.0793x; 1.0063x over previous
.LBB0_1001:
	s_cmp_gt_i32 s34, 9
	s_cselect_b64 s[0:1], -1, 0
	s_cmp_lt_i32 s35, 9
	s_cselect_b64 s[4:5], -1, 0
	s_or_b64 s[0:1], s[0:1], s[4:5]
	s_and_b64 vcc, exec, s[0:1]
	s_cbranch_vccnz .LBB0_1066
	s_mov_b64 s[0:1], 0
	s_load_dword s3, s[92:93], 0xd8
	v_mbcnt_lo_u32_b32 v2, -1, 0
	s_mov_b32 s1, 0
	v_and_b32_e32 v1, 0x3ff, v0
	s_waitcnt lgkmcnt(0)
	v_mov_b32_e32 v3, 0
	s_and_b32 s0, s3, 7
	s_cmp_lg_u32 s0, 0
	s_cselect_b64 s[4:5], -1, 0
	s_cmp_lt_i32 s3, 8
	s_cselect_b64 s[6:7], -1, 0
	s_lshl_b32 s0, s2, 8
	s_lshr_b32 s33, s3, 3
	s_or_b64 s[12:13], s[6:7], s[4:5]
	s_ashr_i32 s38, s2, 3
	s_and_b32 s39, s0, 0x700
	s_mov_b64 s[14:15], 0x4c00000
	s_mov_b32 s40, 0x4c00000
	s_movk_i32 s41, 0x70
	s_mov_b64 s[16:17], 0x2c00000
	s_mov_b64 s[18:19], 0x8c00000
	s_mov_b32 s44, 0x42f00000
	s_mov_b64 s[20:21], 0xac00000
	s_mov_b32 s45, 0xac00000
	s_mov_b64 s[22:23], 0x6c00000
	s_mov_b32 s46, 0x6c00000
	v_mov_b32_e32 v42, 0xff61b1e6
	v_mbcnt_hi_u32_b32 v43, -1, v2
	v_xor_b32_e32 v162, 16, v43
	v_xor_b32_e32 v163, 32, v43
	v_xor_b32_e32 v164, 48, v43
	v_lshlrev_b32_e32 v162, 2, v162
	v_lshlrev_b32_e32 v163, 2, v163
	v_lshlrev_b32_e32 v164, 2, v164
	s_mov_b32 s47, 0
	s_mov_b32 s55, 0
	v_lshrrev_b32_e32 v146, 6, v1
	s_nop 0
	v_readfirstlane_b32 s58, v146
	s_nop 3
	s_cmp_lt_u32 s58, 4
	s_cselect_b32 s58, 1, 0
	s_branch .LBB0_1004

.LBB0_1009:
	s_mov_b64 s[4:5], 0
	s_add_u32 s24, s86, s4
	s_addc_u32 s25, s87, s5
	v_mov_b32_e32 v51, v1
	s_lshr_b32 s4, s26, 4
	s_lshr_b32 s0, s26, 10
	s_and_b32 s4, s4, 48
	s_and_b32 s27, s26, 15
	v_ashrrev_i32_e32 v12, 3, v51
	s_or_b32 s10, s4, s27
	s_lshl_b64 s[4:5], s[0:1], 13
	v_ashrrev_i32_e32 v13, 31, v12
	s_lshl_b32 s6, s26, 2
	v_lshl_add_u64 v[4:5], s[4:5], 0, v[12:13]
	s_and_b32 s48, s6, 0x3c0
	v_lshlrev_b64 v[4:5], 11, v[4:5]
	s_lshl_b32 s6, s48, 1
	s_mov_b32 s7, s1
	v_lshl_add_u64 v[4:5], s[24:25], 0, v[4:5]
	v_lshlrev_b32_e32 v2, 4, v51
	v_lshl_add_u64 v[4:5], v[4:5], 0, s[6:7]
	v_and_b32_e32 v6, 0x70, v2
	v_mov_b32_e32 v7, v3
	v_lshl_add_u64 v[4:5], v[4:5], 0, v[6:7]
	v_lshl_add_u64 v[36:37], v[4:5], 0, s[16:17]
	v_add_u32_e32 v4, s48, v12
	v_ashrrev_i32_e32 v5, 31, v4
	v_lshlrev_b64 v[4:5], 15, v[4:5]
	v_lshl_add_u64 v[4:5], s[24:25], 0, v[4:5]
	s_lshl_b64 s[8:9], s[0:1], 14
	s_lshl_b32 s0, s10, 1
	v_lshl_add_u64 v[4:5], v[4:5], 0, s[8:9]
	s_or_b32 s28, s0, 1
	v_ashrrev_i32_e32 v13, 6, v51
	v_lshl_add_u64 v[4:5], v[4:5], 0, v[6:7]
	s_lshl_b32 s0, s28, 17
	v_and_b32_e32 v53, 15, v51
	v_lshlrev_b32_e32 v48, 4, v13
	v_lshl_add_u64 v[38:39], v[4:5], 0, s[18:19]
	v_lshl_add_u64 v[4:5], v[36:37], 0, s[0:1]
	s_lshl_b32 s0, s28, 7
	v_or_b32_e32 v54, v48, v53
	s_lshl_b32 s8, s10, 7
	v_lshl_add_u64 v[8:9], v[38:39], 0, s[0:1]
	v_add_u32_e32 v14, s8, v54
	v_mov_b64_e32 v[110:111], v[4:5]
	s_nop 0
	v_mov_b64_e32 v[112:113], v[8:9]
	v_ashrrev_i32_e32 v15, 31, v14
	v_lshl_add_u64 v[14:15], s[4:5], 0, v[14:15]
	v_lshlrev_b64 v[16:17], 11, v[14:15]
	v_lshl_add_u64 v[16:17], s[24:25], 0, v[16:17]
	v_lshl_add_u64 v[16:17], v[16:17], 0, s[6:7]
	v_and_b32_e32 v2, 48, v51
	v_lshl_add_u64 v[16:17], v[16:17], 0, v[2:3]
	v_lshl_add_u64 v[18:19], v[16:17], 0, s[14:15]
	v_add_co_u32_e32 v16, vcc, s40, v16
	s_lshl_b32 s0, s10, 18
	s_nop 0
	v_addc_co_u32_e32 v17, vcc, 0, v17, vcc
	v_mov_b64_e32 v[114:115], v[16:17]
	v_mov_b64_e32 v[116:117], v[18:19]
	v_lshl_add_u64 v[16:17], v[36:37], 0, s[0:1]
	s_lshl_b32 s0, s10, 8
	v_lshl_add_u64 v[18:19], v[38:39], 0, s[0:1]
	v_mov_b64_e32 v[92:93], v[16:17]
	v_mov_b64_e32 v[94:95], v[18:19]
	s_cmp_eq_u32 s55, 0
	s_cbranch_scc1 .Lat_doload
	s_waitcnt vmcnt(4)
	v_mov_b32_e32 v4, v118
	v_mov_b32_e32 v5, v119
	v_mov_b32_e32 v6, v120
	v_mov_b32_e32 v7, v121
	v_mov_b32_e32 v8, v122
	v_mov_b32_e32 v9, v123
	v_mov_b32_e32 v10, v124
	v_mov_b32_e32 v11, v125
	v_mov_b32_e32 v20, v126
	v_mov_b32_e32 v21, v127
	v_mov_b32_e32 v22, v128
	v_mov_b32_e32 v23, v129
	v_mov_b32_e32 v24, v130
	v_mov_b32_e32 v25, v131
	v_mov_b32_e32 v26, v132
	v_mov_b32_e32 v27, v133
	v_mov_b32_e32 v28, v84
	v_mov_b32_e32 v29, v85
	v_mov_b32_e32 v30, v86
	v_mov_b32_e32 v31, v87
	v_mov_b32_e32 v32, v88
	v_mov_b32_e32 v33, v89
	v_mov_b32_e32 v34, v90
	v_mov_b32_e32 v35, v91
	s_branch .Lat_loaded2
.Lat_doload:
	global_load_dwordx4 v[4:7], v[110:111], off
	global_load_dwordx4 v[8:11], v[112:113], off
	global_load_dwordx4 v[20:23], v[114:115], off
	global_load_dwordx4 v[24:27], v[116:117], off offset:64
	global_load_dwordx4 v[28:31], v[92:93], off
	global_load_dwordx4 v[32:35], v[94:95], off

.Lat_loaded2:
	v_lshrrev_b32_e32 v17, 1, v51
	v_ashrrev_i32_e32 v18, 5, v51
	v_and_b32_e32 v17, 48, v17
	v_and_b32_e32 v18, -4, v18
	v_and_b32_e32 v19, 3, v12
	v_lshlrev_b32_e32 v40, 7, v12
	v_xor_b32_e32 v12, v12, v51
	v_add_u32_e32 v17, v17, v18
	v_lshlrev_b32_e32 v12, 4, v12
	v_or_b32_e32 v18, v17, v19
	v_bitop3_b32 v17, v17, v51, v19 bitop3:0x36
	v_and_or_b32 v45, v12, s41, v40
	v_lshlrev_b32_e32 v12, 7, v18
	v_lshlrev_b32_e32 v17, 4, v17
	v_and_or_b32 v46, v17, s41, v12
	v_bfe_u32 v44, v51, 4, 2
	v_add_u32_e32 v12, 0, v46
	v_add_u32_e32 v18, 0, v45
	v_and_b32_e32 v16, 63, v51
	s_bfe_u32 s0, s26, 0x20008
	v_sub_u32_e32 v2, v54, v2
	v_lshlrev_b64 v[40:41], 10, v[14:15]
	v_lshl_add_u32 v47, v13, 2, 0
	v_add_u32_e32 v48, s8, v48
	v_cmp_eq_u32_e64 s[8:9], 0, v16
	s_lshl_b32 s50, s0, 11
	s_lshl_b32 s0, s0, 5
	s_lshl_b32 s26, s27, 1
	v_subrev_u32_e32 v54, 64, v2
	s_lshl_b32 s63, s58, 6
	v_add_u32_e32 v54, s63, v54
	ds_write_b128 v12, v[4:7]
	ds_write_b128 v18, v[8:11] offset:8192
	v_add_u32_e32 v146, 0x4000, v46
	v_add_u32_e32 v147, 0x4000, v45
	ds_write_b128 v146, v[28:31]
	ds_write_b128 v147, v[32:35] offset:8192
	s_cmp_lt_u32 s28, 2
	s_cbranch_scc1 .Lat_not2
	s_add_i32 s62, s28, -2
	s_mov_b32 s63, 0
	s_lshl_b64 s[64:65], s[62:63], 17
	v_lshl_add_u64 v[146:147], v[36:37], 0, s[64:65]
	global_load_dwordx4 v[28:31], v[146:147], off
	s_lshl_b32 s64, s62, 7
	s_mov_b32 s65, 0
	v_lshl_add_u64 v[146:147], v[38:39], 0, s[64:65]
	global_load_dwordx4 v[32:35], v[146:147], off
.Lat_not2:
	v_xor_b32_e32 v5, 1, v44
	v_cmp_gt_u32_e64 s[10:11], v5, v44
	v_xor_b32_e32 v5, 2, v44
	v_cmp_gt_u32_e64 s[4:5], v5, v44
	v_xor_b32_e32 v5, 3, v44
	v_and_b32_e32 v4, 7, v51
	v_cmp_gt_u32_e64 s[6:7], v5, v44
	v_lshlrev_b32_e32 v5, 1, v44
	v_bitop3_b32 v6, v44, v51, 7 bitop3:0x78
	v_lshlrev_b32_e32 v49, 4, v6
	v_bitop3_b32 v6, v44, v4, 4 bitop3:0x36
	v_bitop3_b32 v4, v5, v4, 1 bitop3:0x36
	v_lshlrev_b32_e32 v50, 4, v6
	v_bitop3_b32 v6, v5, v51, 7 bitop3:0x78
	v_lshlrev_b32_e32 v52, 4, v4
	v_mov_b32_e32 v4, v3
	v_mov_b32_e32 v5, v3
	v_mov_b32_e32 v2, v3
	v_mov_b64_e32 v[10:11], v[4:5]
	v_mov_b64_e32 v[14:15], v[4:5]
	v_mov_b64_e32 v[18:19], v[4:5]
	v_lshlrev_b32_e32 v51, 4, v6
	s_lshl_b32 s49, s27, 7
	s_or_b32 s0, s0, s26
	v_mov_b64_e32 v[8:9], v[2:3]
	v_mov_b64_e32 v[12:13], v[2:3]
	v_mov_b64_e32 v[16:17], v[2:3]
	v_mov_b64_e32 v[6:7], v[4:5]
	v_mov_b32_e32 v56, 0
	v_lshl_add_u32 v53, v53, 7, 0
	s_add_i32 s26, s0, -2
	s_lshl_b32 s53, s28, 3
	s_or_b32 s51, s49, 64
	s_add_i32 s52, s49, 0x80
	v_mov_b32_e32 v55, 1.0
	s_mov_b32 s59, 0
	v_mov_b64_e32 v[4:5], v[2:3]
	s_mov_b32 s55, 0
	s_and_b64 vcc, exec, s[12:13]
	s_cbranch_vccnz .Lat_nopf
	s_cmp_eq_u32 s33, 32
	s_cbranch_scc0 .Lat_nopf
	s_add_i32 s56, s47, 1
	s_mul_i32 s56, s56, s33
	s_add_i32 s56, s56, s38
	s_cmpk_lt_i32 s56, 0x100
	s_cbranch_scc0 .Lat_nopf
	s_mov_b32 s55, 1
	s_mov_b32 s56, 0x400000
	s_mov_b32 s57, 0
	v_lshl_add_u64 v[112:113], v[112:113], 0, s[56:57]
	global_load_dwordx4 v[118:121], v[110:111], off offset:256
	global_load_dwordx4 v[122:125], v[112:113], off
	global_load_dwordx4 v[126:129], v[114:115], off offset:256
	global_load_dwordx4 v[130:133], v[116:117], off offset:320
	v_lshl_add_u64 v[94:95], v[94:95], 0, s[56:57]
	global_load_dwordx4 v[84:87], v[92:93], off offset:256
	global_load_dwordx4 v[88:91], v[94:95], off

.LBB0_1010:
	s_sub_i32 s50, s50, 64
	s_add_i32 s59, s59, 1
	s_cmp_eq_u32 s59, 3
	s_cselect_b32 s59, 0, s59
	s_add_i32 s26, s26, -1
	s_add_i32 s53, s53, -8
	s_add_i32 s0, s52, s50
	s_cmp_eq_u32 s0, 0
	v_add_u32_e32 v54, 64, v54
	s_cselect_b64 s[28:29], -1, 0
	s_andn2_b64 vcc, exec, s[28:29]
	s_cbranch_vccz .LBB0_1026
.LBB0_1011:
	s_add_i32 s0, s49, s50
	s_add_i32 s60, s59, s58
	s_add_i32 s62, s59, 2
	s_cmp_ge_u32 s60, 3
	s_cselect_b32 s63, 3, 0
	s_sub_i32 s60, s60, s63
	s_cmp_ge_u32 s62, 3
	s_cselect_b32 s63, 3, 0
	s_sub_i32 s62, s62, s63
	s_lshl_b32 s60, s60, 14
	s_lshl_b32 s62, s62, 14
	s_lshl_b32 s61, s58, 6
	s_sub_i32 s61, s0, s61
	v_cmp_eq_u32_e32 vcc, 0, v56
	v_mov_b32_e32 v56, 1
	s_and_saveexec_b64 s[28:29], vcc
	s_cbranch_execz .LBB0_1019
	s_add_i32 s30, s61, 64
	s_cmp_lt_i32 s30, 0
	s_cbranch_scc1 .LBB0_1019
	v_cmp_le_i32_e32 vcc, s30, v48
	v_mov_b32_e32 v56, 0
	s_and_saveexec_b64 s[30:31], vcc
	s_cbranch_execz .LBB0_1018
	v_add_u32_e32 v2, s60, v53
	v_add_u32_e32 v76, v2, v49
	v_add_u32_e32 v77, v2, v50
	ds_read_b128 v[56:59], v76
	ds_read_b128 v[60:63], v76 offset:2048
	ds_read_b128 v[64:67], v77
	ds_read_b128 v[72:75], v77 offset:4096
	s_waitcnt lgkmcnt(3)
	v_mfma_f32_16x16x32_bf16 v[56:59], v[56:59], v[20:23], 0
	ds_read_b128 v[68:71], v77 offset:2048
	s_add_i32 s36, s61, 0x7f
	v_cmp_ge_u32_e32 vcc, s36, v48
	s_waitcnt lgkmcnt(2)
	v_mfma_f32_16x16x32_bf16 v[56:59], v[64:67], v[24:27], v[56:59]
	ds_read_b128 v[64:67], v76 offset:4096
	v_mfma_f32_16x16x32_bf16 v[60:63], v[60:63], v[20:23], 0
	s_nop 5
	v_exp_f32_e64 v166, -v56
	v_exp_f32_e64 v167, -v57
	v_exp_f32_e64 v168, -v58
	s_waitcnt lgkmcnt(1)
	v_mfma_f32_16x16x32_bf16 v[60:63], v[68:71], v[24:27], v[60:63]
	ds_read_b128 v[68:71], v76 offset:6144
	ds_read_b128 v[76:79], v77 offset:6144
	v_exp_f32_e64 v169, -v59
	s_waitcnt lgkmcnt(2)
	v_mfma_f32_16x16x32_bf16 v[64:67], v[64:67], v[20:23], 0
	s_nop 2
	v_exp_f32_e64 v170, -v60
	v_exp_f32_e64 v171, -v61
	v_exp_f32_e64 v172, -v62
	v_mfma_f32_16x16x32_bf16 v[146:149], v[72:75], v[24:27], v[64:67]
	v_exp_f32_e64 v173, -v63
	s_waitcnt lgkmcnt(1)
	v_mfma_f32_16x16x32_bf16 v[64:67], v[68:71], v[20:23], 0
	s_waitcnt lgkmcnt(0)
	v_mfma_f32_16x16x32_bf16 v[150:153], v[76:79], v[24:27], v[64:67]
	s_nop 2
	v_exp_f32_e64 v174, -v146
	v_exp_f32_e64 v175, -v147
	v_exp_f32_e64 v176, -v148
	v_exp_f32_e64 v177, -v149
	s_nop 0
	v_exp_f32_e64 v178, -v150
	v_exp_f32_e64 v179, -v151
	v_exp_f32_e64 v180, -v152
	v_exp_f32_e64 v181, -v153
	v_pk_add_f32 v[182:183], v[166:167], 1.0 op_sel_hi:[1,0]
	v_pk_add_f32 v[184:185], v[168:169], 1.0 op_sel_hi:[1,0]
	v_pk_add_f32 v[186:187], v[170:171], 1.0 op_sel_hi:[1,0]
	v_pk_add_f32 v[188:189], v[172:173], 1.0 op_sel_hi:[1,0]
	v_pk_add_f32 v[190:191], v[174:175], 1.0 op_sel_hi:[1,0]
	v_pk_add_f32 v[192:193], v[176:177], 1.0 op_sel_hi:[1,0]
	v_pk_add_f32 v[194:195], v[178:179], 1.0 op_sel_hi:[1,0]
	v_pk_add_f32 v[196:197], v[180:181], 1.0 op_sel_hi:[1,0]
	v_rcp_f32_e32 v198, v182
	v_rcp_f32_e32 v199, v183
	v_rcp_f32_e32 v200, v184
	v_rcp_f32_e32 v201, v185
	v_rcp_f32_e32 v202, v186
	v_rcp_f32_e32 v203, v187
	v_rcp_f32_e32 v204, v188
	v_rcp_f32_e32 v205, v189
	v_rcp_f32_e32 v206, v190
	v_rcp_f32_e32 v207, v191
	v_rcp_f32_e32 v208, v192
	v_rcp_f32_e32 v209, v193
	v_rcp_f32_e32 v210, v194
	v_rcp_f32_e32 v211, v195
	v_rcp_f32_e32 v212, v196
	v_rcp_f32_e32 v213, v197
	s_and_saveexec_b64 s[36:37], vcc
	s_cbranch_execz .Lpk_join
	v_cmp_lt_i32_e64 s[66:67], 0, v54
	v_cmp_lt_i32_e64 s[68:69], 1, v54
	v_cmp_lt_i32_e64 s[70:71], 2, v54
	v_cmp_lt_i32_e64 s[72:73], 3, v54
	v_cndmask_b32_e64 v198, 0, v198, s[66:67]
	v_cndmask_b32_e64 v199, 0, v199, s[68:69]
	v_cndmask_b32_e64 v200, 0, v200, s[70:71]
	v_cndmask_b32_e64 v201, 0, v201, s[72:73]
	v_cmp_lt_i32_e64 s[66:67], 4, v54
	v_cmp_lt_i32_e64 s[68:69], 5, v54
	v_cmp_lt_i32_e64 s[70:71], 6, v54
	v_cmp_lt_i32_e64 s[72:73], 7, v54
	v_cndmask_b32_e64 v202, 0, v202, s[66:67]
	v_cndmask_b32_e64 v203, 0, v203, s[68:69]
	v_cndmask_b32_e64 v204, 0, v204, s[70:71]
	v_cndmask_b32_e64 v205, 0, v205, s[72:73]
	v_cmp_lt_i32_e64 s[66:67], 8, v54
	v_cmp_lt_i32_e64 s[68:69], 9, v54
	v_cmp_lt_i32_e64 s[70:71], 10, v54
	v_cmp_lt_i32_e64 s[72:73], 11, v54
	v_cndmask_b32_e64 v206, 0, v206, s[66:67]
	v_cndmask_b32_e64 v207, 0, v207, s[68:69]
	v_cndmask_b32_e64 v208, 0, v208, s[70:71]
	v_cndmask_b32_e64 v209, 0, v209, s[72:73]
	v_cmp_lt_i32_e64 s[66:67], 12, v54
	v_cmp_lt_i32_e64 s[68:69], 13, v54
	v_cmp_lt_i32_e64 s[70:71], 14, v54
	v_cmp_lt_i32_e64 s[72:73], 15, v54
	v_cndmask_b32_e64 v210, 0, v210, s[66:67]
	v_cndmask_b32_e64 v211, 0, v211, s[68:69]
	v_cndmask_b32_e64 v212, 0, v212, s[70:71]
	v_cndmask_b32_e64 v213, 0, v213, s[72:73]

.LBB0_1019:
	s_or_b64 exec, exec, s[28:29]
	s_cmp_lt_i32 s0, 64
	s_cbranch_scc1 .LBB0_1022
	v_add_u32_e32 v2, s62, v46
	s_waitcnt vmcnt(1)
	ds_write_b128 v2, v[28:31]
	v_add_u32_e32 v2, s62, v45
	s_cmp_lt_i32 s0, 0x80
	s_waitcnt vmcnt(0)
	ds_write_b128 v2, v[32:35] offset:8192
	s_cbranch_scc1 .LBB0_1022
	s_mov_b32 s27, s1
	s_sub_i32 s0, s0, 0x80
	s_lshl_b64 s[28:29], s[26:27], 17
	v_lshl_add_u64 v[32:33], s[0:1], 1, v[38:39]
	v_lshl_add_u64 v[28:29], v[36:37], 0, s[28:29]
	global_load_dwordx4 v[28:31], v[28:29], off
	s_nop 0
	global_load_dwordx4 v[32:35], v[32:33], off
.LBB0_1022:
	s_and_b32 s0, s53, 8
	s_and_saveexec_b64 s[28:29], s[8:9]
	v_lshl_add_u32 v2, s0, 2, v47
	ds_write_b32 v2, v56 offset:49152
	s_or_b64 exec, exec, s[28:29]
	s_lshl_b32 s0, s0, 2
	s_add_i32 s0, s0, 0
	v_mov_b32_e32 v2, s0
	s_waitcnt lgkmcnt(0)
	s_barrier
	ds_read_b128 v[58:61], v2 offset:49152
	ds_read_b128 v[62:65], v2 offset:49168
	s_waitcnt lgkmcnt(1)
	v_and_b32_e32 v2, v59, v58
	v_and_b32_e32 v2, v2, v60
	v_and_b32_e32 v2, v2, v61
	s_waitcnt lgkmcnt(0)
	v_and_b32_e32 v2, v2, v62
	v_and_b32_e32 v2, v2, v63
	v_and_b32_e32 v2, v2, v64
	v_and_b32_e32 v2, v2, v65
	v_cmp_ne_u32_e32 vcc, 0, v2
	s_cbranch_vccz .LBB0_1010
